# LN1 per-column vectors staged in LDS (row loop reads them by ds_read_b128, no store waits), on top of the LN1 statistics / w_down recompute version
# speedup vs baseline: 1.0120x; 1.0029x over previous
; __device__ __forceinline__ unsigned cvt_pk_bf16(float lo, float hi) { unsigned r; asm volatile("v_cvt_pk_bf16_f32 %0, %1, %2" : "=v"(r) : "v"(lo), "v"(hi)); return r; }
; __device__ __forceinline__ void phase_ln(const float* z, float* xo, const float* __restrict__ g, const float* __restrict__ b, const float* __restrict__ sc, const float* __restrict__ sh, bf16_t* __restrict__ u) {
;     ...
;         for (int j = 0; j < 8; ++j) { const int col = j * 256 + 4 * lane;
;             const f32x4 gg = *(const f32x4*)(g + col), bb = *(const f32x4*)(b + col);
;             f32x4 s1 = {0.f, 0.f, 0.f, 0.f}, h1 = {0.f, 0.f, 0.f, 0.f};
;             if (u) { s1 = *(const f32x4*)(sc + col) + 1.0f; h1 = *(const f32x4*)(sh + col); }
; #pragma unroll
;             for (int k = 0; k < 2; ++k) { if (k == 1 && !hasB) continue;
;                 const f32x4 o = (v[k][j] - mean[k]) * rstd[k] * gg + bb;
;                 *(f32x4*)(xo + (size_t)rr[k] * DM + col) = o;
;                 if (u) { const f32x4 m = o * s1 + h1; u32x2 w; w.x = cvt_pk_bf16(m[0], m[1]); w.y = cvt_pk_bf16(m[2], m[3]); *(u32x2*)(u + (size_t)rr[k] * DM + col) = w; } } }
.LBB0_1075:
	s_or_b64 exec, exec, s[0:1]
	ds_read_b128 v[68:71], v252 offset:1024
	ds_read_b128 v[72:75], v252 offset:9216
	ds_read_b128 v[76:79], v252 offset:17408
	v_mov_b32_e32 v177, v176
	v_mov_b32_e32 v24, v176
	v_mov_b32_e32 v25, v176
	s_mov_b64 s[0:1], 0xb828400
	v_pk_mul_f32 v[56:57], v[202:203], v[24:25]
	v_pk_mul_f32 v[64:65], v[66:67], v[176:177]
	v_lshl_add_u64 v[48:49], v[172:173], 0, s[0:1]
	s_waitcnt lgkmcnt(0)
	v_pk_fma_f32 v[66:67], v[56:57], v[70:71], v[74:75]
	v_pk_add_f32 v[32:33], v[78:79], 1.0 op_sel_hi:[1,0]
	v_pk_add_f32 v[40:41], v[76:77], 1.0 op_sel_hi:[1,0]
	ds_read_b128 v[76:79], v252 offset:25600
	v_pk_fma_f32 v[64:65], v[64:65], v[68:69], v[72:73]
	s_waitcnt lgkmcnt(0)
	v_pk_fma_f32 v[48:49], v[66:67], v[32:33], v[78:79]
	v_pk_fma_f32 v[56:57], v[64:65], v[40:41], v[76:77]
	s_nop 0
	v_cvt_pk_bf16_f32 v56, v56, v57
	v_cvt_pk_bf16_f32 v57, v48, v49
	v_add_co_u32_e32 v48, vcc, 0xf828000, v184
	s_nop 1
	v_addc_co_u32_e32 v49, vcc, 0, v185, vcc
	flat_store_dwordx2 v[48:49], v[56:57] offset:512
	s_and_saveexec_b64 s[0:1], s[4:5]
	s_cbranch_execz .LBB0_1077
	v_pk_mul_f32 v[48:49], v[60:61], v[0:1] op_sel_hi:[1,0]
	v_pk_mul_f32 v[56:57], v[62:63], v[0:1] op_sel_hi:[1,0]
	v_pk_fma_f32 v[62:63], v[48:49], v[70:71], v[74:75]
	v_pk_fma_f32 v[60:61], v[56:57], v[68:69], v[72:73]
	v_lshl_add_u64 v[48:49], v[146:147], 0, v[170:171]
	v_pk_fma_f32 v[32:33], v[62:63], v[32:33], v[78:79]
	v_pk_fma_f32 v[40:41], v[60:61], v[40:41], v[76:77]
	v_cvt_pk_bf16_f32 v40, v40, v41
	v_cvt_pk_bf16_f32 v41, v32, v33
	v_lshl_add_u64 v[32:33], v[148:149], 0, v[182:183]
	flat_store_dwordx2 v[32:33], v[40:41]
.LBB0_1077:
	s_or_b64 exec, exec, s[0:1]
	ds_read_b128 v[72:75], v252 offset:18432
	ds_read_b128 v[64:67], v252 offset:2048
	ds_read_b128 v[68:71], v252 offset:10240
	ds_read_b128 v[60:63], v252 offset:26624
	v_pk_mul_f32 v[48:49], v[58:59], v[176:177]
	s_mov_b64 s[0:1], 0xb828800
	v_pk_mul_f32 v[40:41], v[200:201], v[24:25]
	v_add_co_u32_e32 v76, vcc, 0xf828000, v184
	v_lshl_add_u64 v[78:79], v[172:173], 0, s[0:1]
	s_nop 0
	v_addc_co_u32_e32 v77, vcc, 0, v185, vcc
	s_waitcnt lgkmcnt(0)
	v_pk_add_f32 v[32:33], v[72:73], 1.0 op_sel_hi:[1,0]
	v_pk_add_f32 v[24:25], v[74:75], 1.0 op_sel_hi:[1,0]
	v_pk_fma_f32 v[56:57], v[48:49], v[64:65], v[68:69]
	v_pk_fma_f32 v[58:59], v[40:41], v[66:67], v[70:71]
	v_pk_fma_f32 v[48:49], v[56:57], v[32:33], v[60:61]
	v_pk_fma_f32 v[40:41], v[58:59], v[24:25], v[62:63]
	v_cvt_pk_bf16_f32 v48, v48, v49
	s_nop 0
	v_cvt_pk_bf16_f32 v49, v40, v41
	flat_store_dwordx2 v[76:77], v[48:49] offset:1024
	s_and_saveexec_b64 s[0:1], s[4:5]
	s_cbranch_execz .LBB0_1079
	v_pk_mul_f32 v[40:41], v[52:53], v[0:1] op_sel_hi:[1,0]
	v_pk_mul_f32 v[48:49], v[54:55], v[0:1] op_sel_hi:[1,0]
	v_pk_fma_f32 v[54:55], v[40:41], v[66:67], v[70:71]
	v_pk_fma_f32 v[52:53], v[48:49], v[64:65], v[68:69]
	v_lshl_add_u64 v[40:41], v[136:137], 0, v[170:171]
	v_pk_fma_f32 v[24:25], v[54:55], v[24:25], v[62:63]
	v_pk_fma_f32 v[32:33], v[52:53], v[32:33], v[60:61]
	v_cvt_pk_bf16_f32 v32, v32, v33
	v_cvt_pk_bf16_f32 v33, v24, v25
	v_lshl_add_u64 v[24:25], v[150:151], 0, v[182:183]
	flat_store_dwordx2 v[24:25], v[32:33]
.LBB0_1079:
	s_or_b64 exec, exec, s[0:1]
	ds_read_b128 v[52:55], v252 offset:3072
	ds_read_b128 v[56:59], v252 offset:11264
	ds_read_b128 v[60:63], v252 offset:19456
	v_mov_b32_e32 v24, v176
	v_mov_b32_e32 v25, v176
	s_mov_b64 s[0:1], 0xb828c00
	v_pk_mul_f32 v[48:49], v[196:197], v[24:25]
	v_pk_mul_f32 v[66:67], v[50:51], v[176:177]
	v_lshl_add_u64 v[64:65], v[172:173], 0, s[0:1]
	s_waitcnt lgkmcnt(0)
	v_pk_fma_f32 v[50:51], v[48:49], v[54:55], v[58:59]
	v_pk_add_f32 v[32:33], v[62:63], 1.0 op_sel_hi:[1,0]
	v_pk_add_f32 v[40:41], v[60:61], 1.0 op_sel_hi:[1,0]
	ds_read_b128 v[60:63], v252 offset:27648
	v_pk_fma_f32 v[48:49], v[66:67], v[52:53], v[56:57]
	s_waitcnt lgkmcnt(0)
	s_nop 0
	v_pk_fma_f32 v[50:51], v[50:51], v[32:33], v[62:63]
	v_pk_fma_f32 v[48:49], v[48:49], v[40:41], v[60:61]
	s_nop 0
	v_cvt_pk_bf16_f32 v48, v48, v49
	v_cvt_pk_bf16_f32 v49, v50, v51
	v_add_co_u32_e32 v50, vcc, 0xf828000, v184
	s_nop 1
	v_addc_co_u32_e32 v51, vcc, 0, v185, vcc
	flat_store_dwordx2 v[50:51], v[48:49] offset:1536
	s_and_saveexec_b64 s[0:1], s[4:5]
	s_cbranch_execz .LBB0_1081
	v_pk_mul_f32 v[44:45], v[44:45], v[0:1] op_sel_hi:[1,0]
	v_pk_mul_f32 v[48:49], v[46:47], v[0:1] op_sel_hi:[1,0]
	v_pk_fma_f32 v[46:47], v[44:45], v[54:55], v[58:59]
	v_pk_fma_f32 v[44:45], v[48:49], v[52:53], v[56:57]
	v_lshl_add_u64 v[48:49], v[138:139], 0, v[170:171]
	v_pk_fma_f32 v[32:33], v[46:47], v[32:33], v[62:63]
	v_pk_fma_f32 v[40:41], v[44:45], v[40:41], v[60:61]
	v_cvt_pk_bf16_f32 v40, v40, v41
	v_cvt_pk_bf16_f32 v41, v32, v33
	v_lshl_add_u64 v[32:33], v[152:153], 0, v[182:183]
	flat_store_dwordx2 v[32:33], v[40:41]
.LBB0_1081:
	s_or_b64 exec, exec, s[0:1]
	ds_read_b128 v[56:59], v252 offset:20480
	ds_read_b128 v[48:51], v252 offset:4096
	ds_read_b128 v[52:55], v252 offset:12288
	ds_read_b128 v[44:47], v252 offset:28672
	s_mov_b64 s[0:1], 0xb829000
	v_pk_mul_f32 v[40:41], v[194:195], v[24:25]
	v_pk_mul_f32 v[60:61], v[42:43], v[176:177]
	v_add_co_u32_e32 v62, vcc, 0xf828000, v184
	v_lshl_add_u64 v[64:65], v[172:173], 0, s[0:1]
	s_nop 0
	v_addc_co_u32_e32 v63, vcc, 0, v185, vcc
	s_waitcnt lgkmcnt(0)
	v_pk_add_f32 v[32:33], v[56:57], 1.0 op_sel_hi:[1,0]
	v_pk_add_f32 v[24:25], v[58:59], 1.0 op_sel_hi:[1,0]
	v_pk_fma_f32 v[42:43], v[40:41], v[50:51], v[54:55]
	v_pk_fma_f32 v[40:41], v[60:61], v[48:49], v[52:53]
	s_nop 1
	v_pk_fma_f32 v[40:41], v[40:41], v[32:33], v[44:45]
	v_pk_fma_f32 v[42:43], v[42:43], v[24:25], v[46:47]
	v_cvt_pk_bf16_f32 v40, v40, v41
	s_nop 0
	v_cvt_pk_bf16_f32 v41, v42, v43
	flat_store_dwordx2 v[62:63], v[40:41] offset:2048
	s_and_saveexec_b64 s[0:1], s[4:5]
	s_cbranch_execz .LBB0_1083
	v_pk_mul_f32 v[36:37], v[36:37], v[0:1] op_sel_hi:[1,0]
	v_pk_mul_f32 v[40:41], v[38:39], v[0:1] op_sel_hi:[1,0]
	v_pk_fma_f32 v[38:39], v[36:37], v[50:51], v[54:55]
	v_pk_fma_f32 v[36:37], v[40:41], v[48:49], v[52:53]
	v_lshl_add_u64 v[40:41], v[128:129], 0, v[170:171]
	v_pk_fma_f32 v[24:25], v[38:39], v[24:25], v[46:47]
	v_pk_fma_f32 v[32:33], v[36:37], v[32:33], v[44:45]
	v_cvt_pk_bf16_f32 v32, v32, v33
	v_cvt_pk_bf16_f32 v33, v24, v25
	v_lshl_add_u64 v[24:25], v[158:159], 0, v[182:183]
	flat_store_dwordx2 v[24:25], v[32:33]
; __device__ __forceinline__ unsigned cvt_pk_bf16(float lo, float hi) { unsigned r; asm volatile("v_cvt_pk_bf16_f32 %0, %1, %2" : "=v"(r) : "v"(lo), "v"(hi)); return r; }
; __device__ __forceinline__ void phase_ln(const float* z, float* xo, const float* __restrict__ g, const float* __restrict__ b, const float* __restrict__ sc, const float* __restrict__ sh, bf16_t* __restrict__ u) {
;     ...
;         for (int j = 0; j < 8; ++j) { const int col = j * 256 + 4 * lane;
;             const f32x4 gg = *(const f32x4*)(g + col), bb = *(const f32x4*)(b + col);
;             f32x4 s1 = {0.f, 0.f, 0.f, 0.f}, h1 = {0.f, 0.f, 0.f, 0.f};
;             if (u) { s1 = *(const f32x4*)(sc + col) + 1.0f; h1 = *(const f32x4*)(sh + col); }
; #pragma unroll
;             for (int k = 0; k < 2; ++k) { if (k == 1 && !hasB) continue;
;                 const f32x4 o = (v[k][j] - mean[k]) * rstd[k] * gg + bb;
;                 *(f32x4*)(xo + (size_t)rr[k] * DM + col) = o;
;                 if (u) { const f32x4 m = o * s1 + h1; u32x2 w; w.x = cvt_pk_bf16(m[0], m[1]); w.y = cvt_pk_bf16(m[2], m[3]); *(u32x2*)(u + (size_t)rr[k] * DM + col) = w; } } }
.LBB0_1083:
	s_or_b64 exec, exec, s[0:1]
	ds_read_b128 v[36:39], v252 offset:5120
	ds_read_b128 v[40:43], v252 offset:13312
	ds_read_b128 v[44:47], v252 offset:21504
	v_mov_b32_e32 v24, v176
	v_mov_b32_e32 v25, v176
	s_mov_b64 s[0:1], 0xb829400
	v_pk_mul_f32 v[50:51], v[180:181], v[24:25]
	v_pk_mul_f32 v[34:35], v[34:35], v[176:177]
	v_lshl_add_u64 v[54:55], v[172:173], 0, s[0:1]
	s_waitcnt lgkmcnt(0)
	v_pk_fma_f32 v[52:53], v[50:51], v[38:39], v[42:43]
	v_pk_add_f32 v[32:33], v[46:47], 1.0 op_sel_hi:[1,0]
	v_pk_add_f32 v[48:49], v[44:45], 1.0 op_sel_hi:[1,0]
	ds_read_b128 v[44:47], v252 offset:29696
	v_pk_fma_f32 v[50:51], v[34:35], v[36:37], v[40:41]
	s_waitcnt lgkmcnt(0)
	v_pk_fma_f32 v[34:35], v[52:53], v[32:33], v[46:47]
	v_pk_fma_f32 v[50:51], v[50:51], v[48:49], v[44:45]
	s_nop 0
	v_cvt_pk_bf16_f32 v50, v50, v51
	v_cvt_pk_bf16_f32 v51, v34, v35
	v_add_co_u32_e32 v34, vcc, 0xf828000, v184
	s_nop 1
	v_addc_co_u32_e32 v35, vcc, 0, v185, vcc
	flat_store_dwordx2 v[34:35], v[50:51] offset:2560
	s_and_saveexec_b64 s[0:1], s[4:5]
	s_cbranch_execz .LBB0_1085
	v_pk_mul_f32 v[28:29], v[28:29], v[0:1] op_sel_hi:[1,0]
	v_pk_mul_f32 v[34:35], v[30:31], v[0:1] op_sel_hi:[1,0]
	v_pk_fma_f32 v[30:31], v[28:29], v[38:39], v[42:43]
	v_pk_fma_f32 v[28:29], v[34:35], v[36:37], v[40:41]
	v_lshl_add_u64 v[34:35], v[130:131], 0, v[170:171]
	s_nop 1
	v_pk_fma_f32 v[30:31], v[30:31], v[32:33], v[46:47]
	v_pk_fma_f32 v[28:29], v[28:29], v[48:49], v[44:45]
	s_nop 0
	v_cvt_pk_bf16_f32 v28, v28, v29
	v_cvt_pk_bf16_f32 v29, v30, v31
	v_lshl_add_u64 v[30:31], v[160:161], 0, v[182:183]
	flat_store_dwordx2 v[30:31], v[28:29]
.LBB0_1085:
	s_or_b64 exec, exec, s[0:1]
	ds_read_b128 v[40:43], v252 offset:22528
	ds_read_b128 v[32:35], v252 offset:6144
	ds_read_b128 v[36:39], v252 offset:14336
	ds_read_b128 v[28:31], v252 offset:30720
	s_mov_b64 s[0:1], 0xb829800
	v_pk_mul_f32 v[44:45], v[178:179], v[24:25]
	v_pk_mul_f32 v[46:47], v[26:27], v[176:177]
	v_add_co_u32_e32 v48, vcc, 0xf828000, v184
	v_lshl_add_u64 v[50:51], v[172:173], 0, s[0:1]
	s_nop 0
	v_addc_co_u32_e32 v49, vcc, 0, v185, vcc
	s_waitcnt lgkmcnt(0)
	v_pk_add_f32 v[24:25], v[42:43], 1.0 op_sel_hi:[1,0]
	v_pk_add_f32 v[26:27], v[40:41], 1.0 op_sel_hi:[1,0]
	v_pk_fma_f32 v[42:43], v[44:45], v[34:35], v[38:39]
	v_pk_fma_f32 v[40:41], v[46:47], v[32:33], v[36:37]
	s_nop 1
	v_pk_fma_f32 v[40:41], v[40:41], v[26:27], v[28:29]
	v_pk_fma_f32 v[42:43], v[42:43], v[24:25], v[30:31]
	v_cvt_pk_bf16_f32 v40, v40, v41
	s_nop 0
	v_cvt_pk_bf16_f32 v41, v42, v43
	flat_store_dwordx2 v[48:49], v[40:41] offset:3072
	s_and_saveexec_b64 s[0:1], s[4:5]
	s_cbranch_execz .LBB0_1087
	v_pk_mul_f32 v[20:21], v[20:21], v[0:1] op_sel_hi:[1,0]
	v_pk_mul_f32 v[40:41], v[22:23], v[0:1] op_sel_hi:[1,0]
	v_pk_fma_f32 v[22:23], v[20:21], v[34:35], v[38:39]
	v_pk_fma_f32 v[20:21], v[40:41], v[32:33], v[36:37]
	v_lshl_add_u64 v[32:33], v[132:133], 0, v[170:171]
	s_nop 1
	v_pk_fma_f32 v[22:23], v[22:23], v[24:25], v[30:31]
	v_pk_fma_f32 v[20:21], v[20:21], v[26:27], v[28:29]
	s_nop 0
	v_cvt_pk_bf16_f32 v20, v20, v21
	v_cvt_pk_bf16_f32 v21, v22, v23
	v_lshl_add_u64 v[22:23], v[162:163], 0, v[182:183]
	flat_store_dwordx2 v[22:23], v[20:21]
.LBB0_1087:
	s_or_b64 exec, exec, s[0:1]
	ds_read_b128 v[32:35], v252 offset:23552
	ds_read_b128 v[24:27], v252 offset:7168
	ds_read_b128 v[28:31], v252 offset:15360
	ds_read_b128 v[20:23], v252 offset:31744
	v_mov_b32_e32 v36, v176
	v_mov_b32_e32 v37, v176
	s_mov_b64 s[0:1], 0xb829c00
	v_pk_mul_f32 v[40:41], v[18:19], v[176:177]
	v_pk_mul_f32 v[36:37], v[174:175], v[36:37]
	v_lshl_add_u64 v[38:39], v[172:173], 0, s[0:1]
	v_add_co_u32_e32 v42, vcc, 0xf828000, v184
	s_waitcnt lgkmcnt(0)
	v_pk_add_f32 v[18:19], v[34:35], 1.0 op_sel_hi:[1,0]
	v_pk_add_f32 v[32:33], v[32:33], 1.0 op_sel_hi:[1,0]
	v_pk_fma_f32 v[36:37], v[36:37], v[26:27], v[30:31]
	v_pk_fma_f32 v[34:35], v[40:41], v[24:25], v[28:29]
	v_addc_co_u32_e32 v43, vcc, 0, v185, vcc
	s_nop 0
	v_pk_fma_f32 v[34:35], v[34:35], v[32:33], v[20:21]
	v_pk_fma_f32 v[36:37], v[36:37], v[18:19], v[22:23]
	v_cvt_pk_bf16_f32 v34, v34, v35
	s_nop 0
	v_cvt_pk_bf16_f32 v35, v36, v37
	flat_store_dwordx2 v[42:43], v[34:35] offset:3584
	s_and_saveexec_b64 s[0:1], s[4:5]
	s_cbranch_execz .LBB0_1072
	v_pk_mul_f32 v[16:17], v[16:17], v[0:1] op_sel_hi:[1,0]
	v_pk_mul_f32 v[14:15], v[14:15], v[0:1] op_sel_hi:[1,0]
	v_pk_fma_f32 v[16:17], v[16:17], v[26:27], v[30:31]
	v_pk_fma_f32 v[14:15], v[14:15], v[24:25], v[28:29]
	v_lshl_add_u64 v[24:25], v[134:135], 0, v[170:171]
	s_nop 1
	v_pk_fma_f32 v[16:17], v[16:17], v[18:19], v[22:23]
	v_pk_fma_f32 v[14:15], v[14:15], v[32:33], v[20:21]
	s_nop 0
	v_cvt_pk_bf16_f32 v14, v14, v15
	v_cvt_pk_bf16_f32 v15, v16, v17
	v_lshl_add_u64 v[16:17], v[164:165], 0, v[182:183]
	flat_store_dwordx2 v[16:17], v[14:15]
	s_branch .LBB0_1072
